# P5 copy share moved into P1 K loop (one 8 KiB block per iteration, burst placement) + P5 second-round units split 4-way along K
# baseline (speedup 1.0000x reference)
.LBB0_117:
	s_andn2_b64 vcc, exec, s[0:1]
	s_ashr_i32 s0, s2, 3
	v_writelane_b32 v247, s0, 25
	s_cbranch_vccnz .LBB0_236
	v_lshlrev_b32_e32 v245, 4, v222
	s_mul_i32 s88, s92, 26
	s_mov_b32 s97, s88
	s_mov_b32 s88, 0
	s_mov_b32 s94, s88
	s_mov_b32 s88, s94
	s_min_u32 s88, s88, 25
	s_mov_b32 s89, s97
	s_add_i32 s88, s88, s89
	s_min_u32 s88, s88, 0x16ef
	s_lshr_b32 s89, s88, 1
	s_add_i32 s89, s89, 0xe04
	s_mul_i32 s32, s89, 0x8081
	s_lshr_b32 s32, s32, 24
	s_mul_i32 s90, s32, 0x1fe
	s_sub_i32 s89, s89, s90
	s_lshl_b32 s32, s32, 22
	s_lshl_b32 s89, s89, 13
	s_add_u32 s89, s89, s32
	s_bitcmp1_b32 s88, 0
	s_cselect_b32 s90, s84, s82
	s_cselect_b32 s91, s85, s83
	s_add_u32 s90, s90, s89
	s_addc_u32 s91, s91, 0
	s_add_u32 s90, s90, 0x4000
	s_addc_u32 s91, s91, 0
	global_load_dwordx4 v[248:251], v245, s[90:91] nt
	s_mov_b32 s88, 1
	s_mov_b32 s94, s88
	s_cmpk_lt_i32 s92, 0x38e
	v_mov_b32_e32 v8, v222
	s_cselect_b64 s[0:1], -1, 0
	s_cmpk_gt_i32 s92, 0x38d
	s_nop 0
	v_readfirstlane_b32 s4, v8
	s_cbranch_scc1 .LBB0_120
	v_readlane_b32 s3, v247, 18
	s_mul_i32 s2, s3, 0x71
	s_add_i32 s5, s2, 6
	s_mul_i32 s6, s3, 0x72
	v_readlane_b32 s2, v247, 19
	v_readlane_b32 s3, v247, 20
	s_and_b64 s[2:3], s[2:3], exec
	s_cselect_b32 s2, s6, s5
	v_readlane_b32 s3, v247, 25
	s_add_i32 s2, s2, s3
	s_mul_hi_i32 s3, s2, 0x92492493
	s_add_i32 s3, s3, s2
	s_lshr_b32 s5, s3, 31
	s_ashr_i32 s3, s3, 6
	s_add_i32 s3, s3, s5
	s_lshl_b32 s5, s3, 3
	s_sub_i32 s6, 0x41, s5
	s_min_u32 s6, s6, 8
	s_mulk_i32 s3, 0x70
	s_sub_i32 s7, s2, s3
	v_cvt_f32_ubyte0_e32 v1, s6
	v_cvt_f32_i32_e32 v0, s7
	v_rcp_iflag_f32_e32 v2, v1
	s_ashr_i32 s2, s7, 30
	s_or_b32 s10, s2, 1
	v_mul_f32_e32 v2, v0, v2
	v_trunc_f32_e32 v2, v2
	v_fma_f32 v0, -v2, v1, v0
	v_cvt_i32_f32_e32 v2, v2
	v_cmp_ge_f32_e64 s[2:3], |v0|, v1
	s_and_b64 s[2:3], s[2:3], exec
	s_cselect_b32 s2, s10, 0
	v_readfirstlane_b32 s3, v2
	s_add_i32 s3, s3, s2
	s_sext_i32_i8 s2, s3
	s_mul_i32 s3, s3, s6
	s_sub_i32 s3, s7, s3
	s_sext_i32_i8 s3, s3
	s_add_i32 s6, s5, s3

.LBB0_133:
	ds_read_b128 v[146:149], v155
	ds_read_b128 v[158:161], v155 offset:1024
	ds_read_b128 v[162:165], v155 offset:2048
	ds_read_b128 v[166:169], v155 offset:3072
	ds_read_b128 v[170:173], v156
	ds_read_b128 v[174:177], v156 offset:1024
	ds_read_b128 v[178:181], v156 offset:2048
	ds_read_b128 v[182:185], v156 offset:3072
	s_add_u32 s40, s34, 0xfffc0080
	s_addc_u32 s41, s35, -1
	s_cmp_eq_u32 s72, 12
	s_cselect_b32 s43, s3, s41
	s_cselect_b32 s42, s7, s40
	s_cselect_b32 s41, s17, s65
	s_cselect_b32 s40, s19, s64
	v_lshl_add_u64 v[150:151], s[34:35], 0, v[138:139]
	s_add_i32 m0, s50, 0xc000
	ds_read_b128 v[186:189], v157
	ds_read_b128 v[190:193], v157 offset:1024
	ds_read_b128 v[194:197], v157 offset:2048
	ds_read_b128 v[198:201], v157 offset:3072
	ds_read_b128 v[202:205], v157 offset:4096
	ds_read_b128 v[206:209], v157 offset:5120
	ds_read_b128 v[210:213], v157 offset:6144
	ds_read_b128 v[214:217], v157 offset:7168
	global_load_lds_dwordx4 v[150:151], off
	v_lshl_add_u64 v[150:151], s[34:35], 0, v[140:141]
	s_add_i32 m0, s50, 0xe000
	s_nop 0
	global_load_lds_dwordx4 v[150:151], off
	s_waitcnt vmcnt(8)
	s_waitcnt lgkmcnt(0)
	s_barrier
	s_setprio 1
	s_waitcnt lgkmcnt(0)
	v_mfma_f32_16x16x32_bf16 v[124:127], v[146:149], v[186:189], v[124:127]
	v_mfma_f32_16x16x32_bf16 v[120:123], v[162:165], v[186:189], v[120:123]
	v_mfma_f32_16x16x32_bf16 v[108:111], v[146:149], v[194:197], v[108:111]
	v_mfma_f32_16x16x32_bf16 v[104:107], v[162:165], v[194:197], v[104:107]
	v_mfma_f32_16x16x32_bf16 v[92:95], v[146:149], v[202:205], v[92:95]
	v_mfma_f32_16x16x32_bf16 v[88:91], v[162:165], v[202:205], v[88:91]
	s_mov_b32 s88, s94
	s_add_i32 s88, s88, -1
	s_min_u32 s88, s88, 25
	s_mov_b32 s89, s97
	s_add_i32 s88, s88, s89
	s_min_u32 s88, s88, 0x16ef
	s_lshr_b32 s89, s88, 1
	s_add_i32 s89, s89, 0xe04
	s_mul_i32 s32, s89, 0x8081
	s_lshr_b32 s32, s32, 24
	s_mul_i32 s90, s32, 0x1fe
	s_sub_i32 s89, s89, s90
	s_lshl_b32 s32, s32, 22
	s_lshl_b32 s89, s89, 13
	s_add_u32 s89, s89, s32
	s_bitcmp1_b32 s88, 0
	s_cselect_b32 s90, s66, s70
	s_cselect_b32 s91, s67, s71
	s_add_u32 s90, s90, s89
	s_addc_u32 s91, s91, 0
	global_store_dwordx4 v245, v[248:251], s[90:91] nt
	s_mov_b32 s88, s94
	s_min_u32 s88, s88, 25
	s_mov_b32 s89, s97
	s_add_i32 s88, s88, s89
	s_min_u32 s88, s88, 0x16ef
	s_lshr_b32 s89, s88, 1
	s_add_i32 s89, s89, 0xe04
	s_mul_i32 s32, s89, 0x8081
	s_lshr_b32 s32, s32, 24
	s_mul_i32 s90, s32, 0x1fe
	s_sub_i32 s89, s89, s90
	s_lshl_b32 s32, s32, 22
	s_lshl_b32 s89, s89, 13
	s_add_u32 s89, s89, s32
	s_bitcmp1_b32 s88, 0
	s_cselect_b32 s90, s84, s82
	s_cselect_b32 s91, s85, s83
	s_add_u32 s90, s90, s89
	s_addc_u32 s91, s91, 0
	s_add_u32 s90, s90, 0x4000
	s_addc_u32 s91, s91, 0
	global_load_dwordx4 v[248:251], v245, s[90:91] nt
	s_mov_b32 s88, s94
	s_add_i32 s88, s88, 1
	s_mov_b32 s94, s88
	v_mfma_f32_16x16x32_bf16 v[76:79], v[146:149], v[210:213], v[76:79]
	v_mfma_f32_16x16x32_bf16 v[72:75], v[162:165], v[210:213], v[72:75]
	v_mfma_f32_16x16x32_bf16 v[124:127], v[158:161], v[190:193], v[124:127]
	v_mfma_f32_16x16x32_bf16 v[120:123], v[166:169], v[190:193], v[120:123]
	v_mfma_f32_16x16x32_bf16 v[108:111], v[158:161], v[198:201], v[108:111]
	v_mfma_f32_16x16x32_bf16 v[104:107], v[166:169], v[198:201], v[104:107]
	v_mfma_f32_16x16x32_bf16 v[92:95], v[158:161], v[206:209], v[92:95]
	v_mfma_f32_16x16x32_bf16 v[88:91], v[166:169], v[206:209], v[88:91]
	v_mfma_f32_16x16x32_bf16 v[76:79], v[158:161], v[214:217], v[76:79]
	v_mfma_f32_16x16x32_bf16 v[72:75], v[166:169], v[214:217], v[72:75]
	s_setprio 0
	s_setprio 1
	v_mfma_f32_16x16x32_bf16 v[116:119], v[170:173], v[186:189], v[116:119]
	v_mfma_f32_16x16x32_bf16 v[112:115], v[178:181], v[186:189], v[112:115]
	v_mfma_f32_16x16x32_bf16 v[100:103], v[170:173], v[194:197], v[100:103]
	v_mfma_f32_16x16x32_bf16 v[96:99], v[178:181], v[194:197], v[96:99]
	v_mfma_f32_16x16x32_bf16 v[84:87], v[170:173], v[202:205], v[84:87]
	v_mfma_f32_16x16x32_bf16 v[80:83], v[178:181], v[202:205], v[80:83]
	v_mfma_f32_16x16x32_bf16 v[68:71], v[170:173], v[210:213], v[68:71]
	v_mfma_f32_16x16x32_bf16 v[64:67], v[178:181], v[210:213], v[64:67]
	v_mfma_f32_16x16x32_bf16 v[116:119], v[174:177], v[190:193], v[116:119]
	v_mfma_f32_16x16x32_bf16 v[112:115], v[182:185], v[190:193], v[112:115]
	v_mfma_f32_16x16x32_bf16 v[100:103], v[174:177], v[198:201], v[100:103]
	v_mfma_f32_16x16x32_bf16 v[96:99], v[182:185], v[198:201], v[96:99]
	v_mfma_f32_16x16x32_bf16 v[84:87], v[174:177], v[206:209], v[84:87]
	v_mfma_f32_16x16x32_bf16 v[80:83], v[182:185], v[206:209], v[80:83]
	v_mfma_f32_16x16x32_bf16 v[68:71], v[174:177], v[214:217], v[68:71]
	v_mfma_f32_16x16x32_bf16 v[64:67], v[182:185], v[214:217], v[64:67]
	s_setprio 0
	s_barrier
	s_add_i32 s73, s59, s45
	v_lshl_add_u64 v[150:151], s[40:41], 0, v[130:131]
	s_mov_b32 m0, s73
	ds_read_b128 v[186:189], v157 offset:16384
	ds_read_b128 v[190:193], v157 offset:17408
	ds_read_b128 v[194:197], v157 offset:18432
	ds_read_b128 v[198:201], v157 offset:19456
	ds_read_b128 v[202:205], v157 offset:20480
	ds_read_b128 v[206:209], v157 offset:21504
	ds_read_b128 v[210:213], v157 offset:22528
	ds_read_b128 v[214:217], v157 offset:23552
	global_load_lds_dwordx4 v[150:151], off
	s_add_i32 m0, s73, 0x2000
	s_add_u32 s74, s40, 0x40000
	v_lshl_add_u64 v[218:219], s[40:41], 0, v[134:135]
	s_addc_u32 s75, s41, 0
	s_add_i32 s73, s60, s45
	global_load_lds_dwordx4 v[218:219], off
	v_lshl_add_u64 v[220:221], s[74:75], 0, v[130:131]
	s_mov_b32 m0, s73
	v_lshl_add_u64 v[224:225], s[42:43], 0, v[132:133]
	global_load_lds_dwordx4 v[220:221], off
	v_lshl_add_u64 v[220:221], s[74:75], 0, v[134:135]
	s_add_i32 m0, s73, 0x2000
	s_nop 0
	global_load_lds_dwordx4 v[220:221], off
	v_lshl_add_u64 v[220:221], s[42:43], 0, v[128:129]
	s_mov_b32 m0, s50
	s_nop 0
	global_load_lds_dwordx4 v[220:221], off
	s_mov_b32 m0, s51
	s_nop 0
	global_load_lds_dwordx4 v[224:225], off
	s_waitcnt vmcnt(10)
	s_waitcnt lgkmcnt(0)
	s_barrier
	s_setprio 1
	s_waitcnt lgkmcnt(0)
	v_mfma_f32_16x16x32_bf16 v[60:63], v[146:149], v[186:189], v[60:63]
	v_mfma_f32_16x16x32_bf16 v[56:59], v[162:165], v[186:189], v[56:59]
	v_mfma_f32_16x16x32_bf16 v[44:47], v[146:149], v[194:197], v[44:47]
	v_mfma_f32_16x16x32_bf16 v[40:43], v[162:165], v[194:197], v[40:43]
	v_mfma_f32_16x16x32_bf16 v[28:31], v[146:149], v[202:205], v[28:31]
	v_mfma_f32_16x16x32_bf16 v[24:27], v[162:165], v[202:205], v[24:27]
	v_mfma_f32_16x16x32_bf16 v[12:15], v[146:149], v[210:213], v[12:15]
	v_mfma_f32_16x16x32_bf16 v[8:11], v[162:165], v[210:213], v[8:11]
	v_mfma_f32_16x16x32_bf16 v[60:63], v[158:161], v[190:193], v[60:63]
	v_mfma_f32_16x16x32_bf16 v[56:59], v[166:169], v[190:193], v[56:59]
	v_mfma_f32_16x16x32_bf16 v[44:47], v[158:161], v[198:201], v[44:47]
	v_mfma_f32_16x16x32_bf16 v[40:43], v[166:169], v[198:201], v[40:43]
	v_mfma_f32_16x16x32_bf16 v[28:31], v[158:161], v[206:209], v[28:31]
	v_mfma_f32_16x16x32_bf16 v[24:27], v[166:169], v[206:209], v[24:27]
	v_mfma_f32_16x16x32_bf16 v[12:15], v[158:161], v[214:217], v[12:15]
	v_mfma_f32_16x16x32_bf16 v[8:11], v[166:169], v[214:217], v[8:11]
	s_setprio 0
	s_setprio 1
	v_mfma_f32_16x16x32_bf16 v[52:55], v[170:173], v[186:189], v[52:55]
	v_mfma_f32_16x16x32_bf16 v[48:51], v[178:181], v[186:189], v[48:51]
	v_mfma_f32_16x16x32_bf16 v[36:39], v[170:173], v[194:197], v[36:39]
	v_mfma_f32_16x16x32_bf16 v[32:35], v[178:181], v[194:197], v[32:35]
	v_mfma_f32_16x16x32_bf16 v[20:23], v[170:173], v[202:205], v[20:23]
	v_mfma_f32_16x16x32_bf16 v[16:19], v[178:181], v[202:205], v[16:19]
	v_mfma_f32_16x16x32_bf16 v[4:7], v[170:173], v[210:213], v[4:7]
	v_mfma_f32_16x16x32_bf16 v[0:3], v[178:181], v[210:213], v[0:3]
	v_mfma_f32_16x16x32_bf16 v[52:55], v[174:177], v[190:193], v[52:55]
	v_mfma_f32_16x16x32_bf16 v[48:51], v[182:185], v[190:193], v[48:51]
	v_mfma_f32_16x16x32_bf16 v[36:39], v[174:177], v[198:201], v[36:39]
	v_mfma_f32_16x16x32_bf16 v[32:35], v[182:185], v[198:201], v[32:35]
	v_mfma_f32_16x16x32_bf16 v[20:23], v[174:177], v[206:209], v[20:23]
	v_mfma_f32_16x16x32_bf16 v[16:19], v[182:185], v[206:209], v[16:19]
	v_mfma_f32_16x16x32_bf16 v[4:7], v[174:177], v[214:217], v[4:7]
	v_mfma_f32_16x16x32_bf16 v[0:3], v[182:185], v[214:217], v[0:3]
	s_setprio 0
	s_barrier
	s_add_i32 s73, 0, 0x18000
	v_add_u32_e32 v136, s73, v154
	s_add_i32 s74, 0, 0x1c000
	ds_read_b128 v[146:149], v136
	ds_read_b128 v[158:161], v136 offset:1024
	ds_read_b128 v[162:165], v136 offset:2048
	ds_read_b128 v[166:169], v136 offset:3072
	v_add_u32_e32 v136, s74, v154
	ds_read_b128 v[170:173], v136
	ds_read_b128 v[174:177], v136 offset:1024
	ds_read_b128 v[178:181], v136 offset:2048
	ds_read_b128 v[182:185], v136 offset:3072
	s_add_u32 s42, s42, 0x40000
	s_addc_u32 s43, s43, 0
	s_mov_b32 m0, s52
	v_lshl_add_u64 v[226:227], s[42:43], 0, v[128:129]
	ds_read_b128 v[186:189], v157 offset:32768
	ds_read_b128 v[190:193], v157 offset:33792
	ds_read_b128 v[194:197], v157 offset:34816
	ds_read_b128 v[198:201], v157 offset:35840
	ds_read_b128 v[202:205], v157 offset:36864
	ds_read_b128 v[206:209], v157 offset:37888
	ds_read_b128 v[210:213], v157 offset:38912
	ds_read_b128 v[214:217], v157 offset:39936
	global_load_lds_dwordx4 v[226:227], off
	v_lshl_add_u64 v[226:227], s[42:43], 0, v[132:133]
	s_mov_b32 m0, s53
	s_nop 0
	global_load_lds_dwordx4 v[226:227], off
	s_waitcnt vmcnt(10)
	s_waitcnt lgkmcnt(0)
	s_barrier
	s_setprio 1
	s_waitcnt lgkmcnt(0)
	v_mfma_f32_16x16x32_bf16 v[124:127], v[146:149], v[186:189], v[124:127]
	v_mfma_f32_16x16x32_bf16 v[120:123], v[162:165], v[186:189], v[120:123]
	v_mfma_f32_16x16x32_bf16 v[108:111], v[146:149], v[194:197], v[108:111]
	v_mfma_f32_16x16x32_bf16 v[104:107], v[162:165], v[194:197], v[104:107]
	v_mfma_f32_16x16x32_bf16 v[92:95], v[146:149], v[202:205], v[92:95]
	v_mfma_f32_16x16x32_bf16 v[88:91], v[162:165], v[202:205], v[88:91]
	v_mfma_f32_16x16x32_bf16 v[76:79], v[146:149], v[210:213], v[76:79]
	v_mfma_f32_16x16x32_bf16 v[72:75], v[162:165], v[210:213], v[72:75]
	v_mfma_f32_16x16x32_bf16 v[124:127], v[158:161], v[190:193], v[124:127]
	v_mfma_f32_16x16x32_bf16 v[120:123], v[166:169], v[190:193], v[120:123]
	v_mfma_f32_16x16x32_bf16 v[108:111], v[158:161], v[198:201], v[108:111]
	v_mfma_f32_16x16x32_bf16 v[104:107], v[166:169], v[198:201], v[104:107]
	v_mfma_f32_16x16x32_bf16 v[92:95], v[158:161], v[206:209], v[92:95]
	v_mfma_f32_16x16x32_bf16 v[88:91], v[166:169], v[206:209], v[88:91]
	v_mfma_f32_16x16x32_bf16 v[76:79], v[158:161], v[214:217], v[76:79]
	v_mfma_f32_16x16x32_bf16 v[72:75], v[166:169], v[214:217], v[72:75]
	s_setprio 0
	s_setprio 1
	v_mfma_f32_16x16x32_bf16 v[116:119], v[170:173], v[186:189], v[116:119]
	v_mfma_f32_16x16x32_bf16 v[112:115], v[178:181], v[186:189], v[112:115]
	v_mfma_f32_16x16x32_bf16 v[100:103], v[170:173], v[194:197], v[100:103]
	v_mfma_f32_16x16x32_bf16 v[96:99], v[178:181], v[194:197], v[96:99]
	v_mfma_f32_16x16x32_bf16 v[84:87], v[170:173], v[202:205], v[84:87]
	v_mfma_f32_16x16x32_bf16 v[80:83], v[178:181], v[202:205], v[80:83]
	v_mfma_f32_16x16x32_bf16 v[68:71], v[170:173], v[210:213], v[68:71]
	v_mfma_f32_16x16x32_bf16 v[64:67], v[178:181], v[210:213], v[64:67]
	v_mfma_f32_16x16x32_bf16 v[116:119], v[174:177], v[190:193], v[116:119]
	v_mfma_f32_16x16x32_bf16 v[112:115], v[182:185], v[190:193], v[112:115]
	v_mfma_f32_16x16x32_bf16 v[100:103], v[174:177], v[198:201], v[100:103]
	v_mfma_f32_16x16x32_bf16 v[96:99], v[182:185], v[198:201], v[96:99]
	v_mfma_f32_16x16x32_bf16 v[84:87], v[174:177], v[206:209], v[84:87]
	v_mfma_f32_16x16x32_bf16 v[80:83], v[182:185], v[206:209], v[80:83]
	v_mfma_f32_16x16x32_bf16 v[68:71], v[174:177], v[214:217], v[68:71]
	v_mfma_f32_16x16x32_bf16 v[64:67], v[182:185], v[214:217], v[64:67]
	s_setprio 0
	s_barrier
	s_add_i32 s42, s73, s45
	v_lshl_add_u64 v[150:151], v[150:151], 0, s[10:11]
	s_mov_b32 m0, s42
	ds_read_b128 v[186:189], v157 offset:49152
	ds_read_b128 v[190:193], v157 offset:50176
	ds_read_b128 v[194:197], v157 offset:51200
	ds_read_b128 v[198:201], v157 offset:52224
	ds_read_b128 v[202:205], v157 offset:53248
	ds_read_b128 v[206:209], v157 offset:54272
	ds_read_b128 v[210:213], v157 offset:55296
	ds_read_b128 v[214:217], v157 offset:56320
	global_load_lds_dwordx4 v[150:151], off
	s_add_i32 m0, s42, 0x2000
	s_add_u32 s40, s40, 0x40080
	v_lshl_add_u64 v[150:151], v[218:219], 0, s[10:11]
	s_addc_u32 s41, s41, 0
	s_add_i32 s42, s74, s45
	global_load_lds_dwordx4 v[150:151], off
	v_lshl_add_u64 v[150:151], s[40:41], 0, v[130:131]
	s_mov_b32 m0, s42
	s_nop 0
	global_load_lds_dwordx4 v[150:151], off
	v_lshl_add_u64 v[150:151], s[40:41], 0, v[134:135]
	s_add_i32 m0, s42, 0x2000
	s_nop 0
	global_load_lds_dwordx4 v[150:151], off
	v_lshl_add_u64 v[150:151], v[220:221], 0, s[10:11]
	s_mov_b32 m0, s57
	s_nop 0
	global_load_lds_dwordx4 v[150:151], off
	v_lshl_add_u64 v[150:151], v[224:225], 0, s[10:11]
	s_mov_b32 m0, s58
	s_nop 0
	global_load_lds_dwordx4 v[150:151], off
	s_waitcnt vmcnt(8)
	s_waitcnt lgkmcnt(0)
	s_barrier
	s_setprio 1
	s_waitcnt lgkmcnt(0)
	v_mfma_f32_16x16x32_bf16 v[60:63], v[146:149], v[186:189], v[60:63]
	v_mfma_f32_16x16x32_bf16 v[56:59], v[162:165], v[186:189], v[56:59]
	v_mfma_f32_16x16x32_bf16 v[44:47], v[146:149], v[194:197], v[44:47]
	v_mfma_f32_16x16x32_bf16 v[40:43], v[162:165], v[194:197], v[40:43]
	v_mfma_f32_16x16x32_bf16 v[28:31], v[146:149], v[202:205], v[28:31]
	v_mfma_f32_16x16x32_bf16 v[24:27], v[162:165], v[202:205], v[24:27]
	v_mfma_f32_16x16x32_bf16 v[12:15], v[146:149], v[210:213], v[12:15]
	v_mfma_f32_16x16x32_bf16 v[8:11], v[162:165], v[210:213], v[8:11]
	v_mfma_f32_16x16x32_bf16 v[60:63], v[158:161], v[190:193], v[60:63]
	v_mfma_f32_16x16x32_bf16 v[56:59], v[166:169], v[190:193], v[56:59]
	v_mfma_f32_16x16x32_bf16 v[44:47], v[158:161], v[198:201], v[44:47]
	v_mfma_f32_16x16x32_bf16 v[40:43], v[166:169], v[198:201], v[40:43]
	v_mfma_f32_16x16x32_bf16 v[28:31], v[158:161], v[206:209], v[28:31]
	v_mfma_f32_16x16x32_bf16 v[24:27], v[166:169], v[206:209], v[24:27]
	v_mfma_f32_16x16x32_bf16 v[12:15], v[158:161], v[214:217], v[12:15]
	v_mfma_f32_16x16x32_bf16 v[8:11], v[166:169], v[214:217], v[8:11]
	s_setprio 0
	s_setprio 1
	v_mfma_f32_16x16x32_bf16 v[52:55], v[170:173], v[186:189], v[52:55]
	v_mfma_f32_16x16x32_bf16 v[48:51], v[178:181], v[186:189], v[48:51]
	v_mfma_f32_16x16x32_bf16 v[36:39], v[170:173], v[194:197], v[36:39]
	v_mfma_f32_16x16x32_bf16 v[32:35], v[178:181], v[194:197], v[32:35]
	v_mfma_f32_16x16x32_bf16 v[20:23], v[170:173], v[202:205], v[20:23]
	v_mfma_f32_16x16x32_bf16 v[16:19], v[178:181], v[202:205], v[16:19]
	v_mfma_f32_16x16x32_bf16 v[4:7], v[170:173], v[210:213], v[4:7]
	v_mfma_f32_16x16x32_bf16 v[0:3], v[178:181], v[210:213], v[0:3]
	v_mfma_f32_16x16x32_bf16 v[52:55], v[174:177], v[190:193], v[52:55]
	v_mfma_f32_16x16x32_bf16 v[48:51], v[182:185], v[190:193], v[48:51]
	v_mfma_f32_16x16x32_bf16 v[36:39], v[174:177], v[198:201], v[36:39]
	v_mfma_f32_16x16x32_bf16 v[32:35], v[182:185], v[198:201], v[32:35]
	v_mfma_f32_16x16x32_bf16 v[20:23], v[174:177], v[206:209], v[20:23]
	v_mfma_f32_16x16x32_bf16 v[16:19], v[182:185], v[206:209], v[16:19]
	v_mfma_f32_16x16x32_bf16 v[4:7], v[174:177], v[214:217], v[4:7]
	v_mfma_f32_16x16x32_bf16 v[0:3], v[182:185], v[214:217], v[0:3]
	s_setprio 0
	s_barrier
	s_add_i32 s72, s72, 2
	s_add_u32 s34, s34, 0x100
	s_addc_u32 s35, s35, 0
	s_add_u32 s64, s64, 0x100
	s_addc_u32 s65, s65, 0
	s_cmp_gt_u32 s72, 13
	s_cbranch_scc0 .LBB0_133
	s_and_b64 vcc, exec, s[12:13]
	s_cbranch_vccz .LBB0_136
	s_barrier

.LBB0_235:
	s_mov_b32 s88, s94
	s_add_i32 s88, s88, -1
	s_min_u32 s88, s88, 25
	s_mov_b32 s89, s97
	s_add_i32 s88, s88, s89
	s_min_u32 s88, s88, 0x16ef
	s_lshr_b32 s89, s88, 1
	s_add_i32 s89, s89, 0xe04
	s_mul_i32 s32, s89, 0x8081
	s_lshr_b32 s32, s32, 24
	s_mul_i32 s90, s32, 0x1fe
	s_sub_i32 s89, s89, s90
	s_lshl_b32 s32, s32, 22
	s_lshl_b32 s89, s89, 13
	s_add_u32 s89, s89, s32
	s_bitcmp1_b32 s88, 0
	s_cselect_b32 s90, s66, s70
	s_cselect_b32 s91, s67, s71
	s_add_u32 s90, s90, s89
	s_addc_u32 s91, s91, 0
	global_store_dwordx4 v245, v[248:251], s[90:91] nt
	s_waitcnt vmcnt(0)
	s_barrier

.LBB0_661:
	s_lshl_b32 s64, s88, 11
	v_or_b32_e32 v0, s64, v222
	s_cmp_gt_i32 s88, 3
	v_add_u32_e32 v0, 0x1be800, v0
	s_mov_b32 s2, 0
	s_cselect_b64 s[0:1], -1, 0
	v_cmp_gt_i32_e32 vcc, s2, v0
	s_and_b64 s[2:3], s[0:1], vcc
	s_and_saveexec_b64 s[0:1], s[2:3]
	s_cbranch_execz .LBB0_664
	v_readlane_b32 s2, v247, 15
	v_add_u32_e32 v0, s64, v222
	s_add_i32 s6, s2, 0xffffe000
	v_add_u32_e32 v0, 0x1be800, v0
	s_mov_b64 s[2:3], 0
	s_mov_b32 s7, 0x80808081
	s_mov_b32 s8, 0xfffc0400
	s_movk_i32 s9, 0x4000
	s_mov_b32 s10, 0x32f7ff
